# move W_in_c[1] and W_up[2] bf16 conversion from the prologue into the layer-1 recurrence-phase idle slot
# baseline (speedup 1.0000x reference)
; #define LAS __attribute__((address_space(3)))
; template <class T> __device__ __forceinline__ T* as_global(T* p) { return (T*)(T GAS*)(unsigned long long)p; }
; __device__ __forceinline__ int lau_v(int x) { asm volatile("" : "+v"(x)); return x; }
; __device__ __forceinline__ TrMat conv_mat(KArgs* A_k, unsigned char* ws, int id) {
;     TrMat t{};
;     if (id < CM_WQB) { const int i = id - CM_WINA; t = TrMat{as_global(A_k->in[I_WINA]) + (size_t)i * DM * INA, DM, INA, as_global(A_k->in[I_GMIX]) + (size_t)(2 * i) * DM, (bf16_t*)(ws + WS_WINA) + (size_t)i * INA_PAD * DM, (size_t)DM, 1, nullptr}; }
;     else if (id < CM_WUK) { const int i = id - CM_WQB; t = TrMat{as_global(A_k->in[I_WQB]) + (size_t)i * QR * 1536, QR, 1536, as_global(A_k->in[I_GQA]) + (size_t)i * QR, (bf16_t*)(ws + WS_WQB) + (size_t)i * 1536 * QR, (size_t)QR, 2, nullptr}; }
;     else if (id < CM_WUV) { const int i = id - CM_WUK; t = TrMat{as_global(A_k->in[I_WUK]) + (size_t)i * KVR * 1024, KVR, 1024, nullptr, (bf16_t*)(ws + WS_WKV) + (size_t)i * 2048 * KVR, (size_t)KVR, 0, nullptr}; }
;     else if (id < CM_WPOOL) { const int i = id - CM_WUV; t = TrMat{as_global(A_k->in[I_WUV]) + (size_t)i * KVR * 1024, KVR, 1024, nullptr, (bf16_t*)(ws + WS_WKV) + (size_t)i * 2048 * KVR + (size_t)1024 * KVR, (size_t)KVR, 0, nullptr}; }
;     else if (id < CM_WOUTA) { const int ig = id - CM_WPOOL; t = TrMat{as_global(A_k->in[I_WPOOL]) + (size_t)ig * 256 * 256, 256, 256, nullptr, (bf16_t*)(ws + WS_WPOOL) + (size_t)ig * 256 * 256, (size_t)256, 0, as_global(A_k->in[I_PSCALE]) + (size_t)ig * 256}; }
;     else if (id < CM_WINC) { const int i = id - CM_WOUTA; t = TrMat{as_global(A_k->in[I_WOUTA]) + (size_t)i * DM * DM, DM, DM, nullptr, (bf16_t*)(ws + WS_WOUTA) + (size_t)i * DM * DM, (size_t)DM, 0, nullptr}; }
; __device__ __forceinline__ void conv_run(const Frame& F, KArgs* A_k, unsigned mask, int widx, int nw) {
;     LAS float* scr = (LAS float*)(F.lds + F.wave * 16384);
;     const int lane = lau_v(lane_id()); unsigned char* ws = lau_s(A_k->ws);
;     int first = widx;
; #pragma unroll 1
;     for (int id = 0; id < CM_FILL; ++id) {
;         if (!((mask >> id) & 1u)) continue;
;         const TrMat t = conv_mat(A_k, ws, id); const int n = (t.K / 64) * (t.N / 32);
;         int it = first;
; #pragma unroll 1
;         for (; it < n; it += nw) tr_mat_item(t, it, scr, lane);
;         first = it - n;
;     }
.LBB0_9:
	s_lshl_b32 s2, 1, s52
	s_and_b32 s2, s2, 0x40450f55
	s_cmp_eq_u32 s2, 0
	s_cbranch_scc1 .LBB0_8
	s_cmp_gt_u32 s52, 1
	s_mov_b64 s[4:5], -1
	s_cbranch_scc0 .LBB0_22
	s_cmp_gt_u32 s52, 3
	s_cbranch_scc0 .LBB0_42
	s_cmp_gt_u32 s52, 5
	s_cbranch_scc0 .LBB0_39
	s_cmp_gt_u32 s52, 7
	s_cbranch_scc0 .LBB0_36
	s_cmp_gt_u32 s52, 15
	s_mov_b64 s[22:23], -1
	s_cbranch_scc0 .LBB0_34
	s_cmp_gt_u32 s52, 17
	s_cbranch_scc0 .LBB0_31
	s_cmp_gt_u32 s52, 19
	s_cbranch_scc0 .LBB0_28
	s_cmp_gt_u32 s52, 21
	s_cbranch_scc0 .LBB0_25
	s_cmp_gt_u32 s52, 25
	s_cbranch_scc0 .LBB0_20
	s_load_dwordx2 s[2:3], s[0:1], 0xd0
	s_sub_i32 s4, s52, 26
	s_mul_i32 s14, s4, 0x2c00000
	s_mul_hi_u32 s5, s4, 0x2c00000
	s_mul_hi_u32 s17, s4, 0x1600000
	s_waitcnt lgkmcnt(0)
	s_add_u32 s2, s2, s14
	s_addc_u32 s3, s3, s5
	s_mul_i32 s4, s4, 0x1600000
	s_add_u32 s16, s7, s4
	s_addc_u32 s17, s9, s17
	s_mov_b64 s[4:5], 0

; #define LAS __attribute__((address_space(3)))
; template <class T> __device__ __forceinline__ T* lau_s(T* p) { asm volatile("" : "+s"(p)); return as_global(p); }
; __device__ __forceinline__ int lau_v(int x) { asm volatile("" : "+v"(x)); return x; }
; __device__ __forceinline__ int lane_id() { int l; asm volatile("v_mbcnt_lo_u32_b32 %0, -1, 0\n\tv_mbcnt_hi_u32_b32 %0, -1, %0" : "=v"(l)); return l; }
; __device__ __forceinline__ KArgs* kargs() { KArgs* p = (KArgs*)__builtin_amdgcn_kernarg_segment_ptr(); asm volatile("" : "+s"(p)); return p; }
; __device__ __forceinline__ void conv_run(const Frame& F, KArgs* A_k, unsigned mask, int widx, int nw) {
;     LAS float* scr = (LAS float*)(F.lds + F.wave * 16384);
;     const int lane = lau_v(lane_id()); unsigned char* ws = lau_s(A_k->ws);
;     int first = widx;
; #pragma unroll 1
;     for (int id = 0; id < CM_FILL; ++id) {
;         if (!((mask >> id) & 1u)) continue;
;         const TrMat t = conv_mat(A_k, ws, id); const int n = (t.K / 64) * (t.N / 32);
;         int it = first;
; #pragma unroll 1
;         for (; it < n; it += nw) tr_mat_item(t, it, scr, lane);
; __global__ void __launch_bounds__(NWAVES * 64, 2) mk_fwd(Args args) {
;     ...
;             if (RUN()) { gla_phase(F, kargs(), li);
;                 { const unsigned job = layer == 1 ? CJ_GLA1 : CJ_GLA3;
;                     if (F.G == 256) { if ((int)blockIdx.x >= 128) conv_run(F, kargs(), job, ((int)blockIdx.x - 128) * NWAVES + F.wave, 128 * NWAVES); }
;                     else conv_run(F, kargs(), job, (int)blockIdx.x * NWAVES + F.wave, F.G * NWAVES); } }
.LBB0_446:
	v_readlane_b32 s0, v255, 22
	v_readlane_b32 s1, v255, 23
	s_cmp_eq_u32 s0, 1
	s_mov_b32 s0, 0x818af0aa
	v_readlane_b32 s74, v255, 14
	v_readlane_b32 s80, v255, 24
	v_readlane_b32 s92, v255, 17
	s_cselect_b32 s26, s0, 0x22000000
	s_mov_b64 s[0:1], -1
	s_and_b64 vcc, exec, s[70:71]
	v_readlane_b32 s75, v255, 15
	v_readlane_b32 s81, v255, 25
	v_readlane_b32 s78, v255, 26
	v_readlane_b32 s93, v255, 18
	v_readlane_b32 s82, v255, 27
	v_readlane_b32 s94, v255, 28
	s_movk_i32 s95, 0x121
	s_movk_i32 s38, 0x47ff
	s_cbranch_vccz .LBB0_546
	s_mov_b64 s[0:1], s[74:75]
	v_readlane_b32 s2, v255, 8
	s_waitcnt vmcnt(0)
	v_mbcnt_lo_u32_b32 v41, -1, 0
	v_mbcnt_hi_u32_b32 v41, -1, v41
	s_add_i32 s27, s82, s2
	s_lshl_b32 s2, s82, 14
	s_load_dwordx2 s[6:7], s[0:1], 0xe0
	s_lshl_b32 s28, s53, 3
	s_add_i32 s2, s55, s2
	s_waitcnt lgkmcnt(0)
	s_add_u32 s29, s6, 0x14b00000
	s_addc_u32 s30, s7, 0
	s_add_u32 s31, s6, 0x9b00000
	s_addc_u32 s33, s7, 0
	s_add_u32 s34, s6, 0x8b00000
	s_addc_u32 s35, s7, 0
	s_add_u32 s36, s6, 0x4b00000
	s_addc_u32 s37, s7, 0
	s_add_u32 s38, s6, 0x3b00000
	s_addc_u32 s39, s7, 0
	s_add_u32 s40, s6, 0x3a00000
	s_addc_u32 s41, s7, 0
	s_add_u32 s42, s6, 0x1600000
	s_addc_u32 s43, s7, 0
	s_add_u32 s44, s6, 0x1300000
	v_lshlrev_b32_e32 v0, 2, v41
	v_lshlrev_b32_e32 v2, 3, v41
	s_addc_u32 s45, s7, 0
	v_ashrrev_i32_e32 v34, 3, v41
	v_and_b32_e32 v0, 28, v0
	s_movk_i32 s3, 0x84
	v_and_b32_e32 v2, 56, v2
	s_add_u32 s46, s6, 0x100000
	v_lshl_add_u32 v3, v0, 2, s2
	v_mul_lo_u32 v4, v34, s3
	v_mul_u32_u24_e32 v5, 0x84, v2
	v_lshlrev_b32_e32 v6, 2, v34
	s_addc_u32 s47, s7, 0
	v_add3_u32 v45, s2, v5, v6
	v_ashrrev_i32_e32 v35, 31, v34
	s_mov_b32 s48, 0
	v_lshlrev_b32_e32 v36, 2, v0
	v_lshlrev_b32_e32 v0, 1, v2
	v_add_u32_e32 v46, v3, v4
	s_mov_b32 s49, s27
	s_branch .LBB0_450
